# N2 fast path: lane-max tree replaced by a row-sum overflow test plus a mask-derived no-reference test
# baseline (speedup 1.0000x reference)
; __device__ void phaseN2_task(const Params& p, int task, char* lds, bf16_t* ydst, int ystride, volatile unsigned* uex, char* ldsb) {
;     ...
;     {
;         const int lo = (t0 & ~31) - 511;
;         const int jb0 = lo > 0 ? (lo >> 6) : 0;
;         const int kkey = t512 >> 3, kch = (t512 & 7) * 8;
;         const int vd = t512 >> 3, vch = (t512 & 7) * 8;
;         const bf16_t* vtb = (const bf16_t*)(p.ws + OFF_VT) + ((size_t)(b * 2 + g) * 64 + vd) * SEQ + vch;
;         u32x4 kreg, vreg;
;         int br = 0, j = 0;
;         {
;             const bf16_t* kb = Z + (rowb + 0) * ZC + ZKS + g * 64;
;             kreg = *(const u32x4*)(kb + (size_t)kkey * ZC + kch);
;             vreg = *(const u32x4*)(vtb);
;         }
;         f32x4 O[2][4];
;         float m[2] = {-1e30f, -1e30f}, l[2] = {0.f, 0.f};
; #pragma unroll
;         for (int x = 0; x < 2; x++)
; #pragma unroll
;             for (int dt = 0; dt < 4; dt++) O[x][dt] = (f32x4){0.f, 0.f, 0.f, 0.f};
.LBB0_616:
	s_or_b64 exec, exec, s[4:5]
	s_lshl_b32 s4, 2, s76
	s_add_i32 s4, s4, -1
	s_cmp_lg_u32 s76, 31
	s_cselect_b32 s10, s4, -2
	s_add_i32 s4, s1, 0xfffffe01
	s_ashr_i32 s11, s4, 6
	s_lshl_b32 s0, s0, 18
	s_add_u32 s4, s92, s0
	v_ashrrev_i32_e32 v49, 31, v48
	s_addc_u32 s5, s93, 0
	s_mul_i32 s0, s88, 0x2700
	v_lshlrev_b64 v[16:17], 12, v[48:49]
	s_add_u32 s0, s90, s0
	v_lshlrev_b32_e32 v25, 3, v124
	v_lshl_add_u64 v[16:17], s[4:5], 0, v[16:17]
	s_addc_u32 s5, s91, 0
	s_lshl_b32 s12, s89, 6
	s_lshl_b32 s4, s89, 7
	v_and_b32_e32 v34, 56, v25
	s_add_u32 s4, s0, s4
	s_movk_i32 s0, 0x1380
	v_lshlrev_b32_e32 v88, 1, v34
	s_addc_u32 s5, s5, 0
	v_mad_i64_i32 v[94:95], s[6:7], v48, s0, 0
	v_lshl_add_u64 v[36:37], v[16:17], 0, v[88:89]
	v_lshl_add_u64 v[16:17], v[94:95], 1, s[4:5]
	v_lshl_add_u64 v[16:17], v[16:17], 0, v[88:89]
	s_movk_i32 s0, 0x2000
	v_add_co_u32_e32 v16, vcc, s0, v16
	s_mov_b32 s0, 0xf800000
	s_nop 0
	v_addc_co_u32_e32 v17, vcc, 0, v17, vcc
	v_mov_b32_e32 v93, v91
	v_add_co_u32_e32 v20, vcc, s0, v36
	s_waitcnt lgkmcnt(0)
	s_barrier
	flat_load_dword v33, v[90:91] sc0 sc1
	s_waitcnt vmcnt(0)
	flat_load_dword v35, v[92:93] sc0 sc1
	s_waitcnt vmcnt(0)
	v_addc_co_u32_e32 v21, vcc, 0, v37, vcc
	global_load_dwordx4 v[16:19], v[16:17], off offset:512
	s_nop 0
	global_load_dwordx4 v[20:23], v[20:21], off
	v_and_b32_e32 v26, 7, v124
	v_lshlrev_b32_e32 v38, 7, v48
	v_bitop3_b32 v27, v75, v124, 7 bitop3:0x78
	v_bitop3_b32 v40, v25, 56, v124 bitop3:0x48
	v_bitop3_b32 v42, v75, v26, 4 bitop3:0x36
	v_lshlrev_b32_e32 v39, 4, v48
	v_lshlrev_b32_e32 v28, 4, v74
	v_lshlrev_b32_e32 v29, 1, v129
	v_mov_b32_e32 v24, 0
	v_lshlrev_b32_e32 v41, 4, v27
	v_lshl_or_b32 v136, v40, 1, v38
	v_lshlrev_b32_e32 v40, 4, v42
	s_mov_b64 s[4:5], 0xf800000
	s_cmpk_gt_i32 s1, 0x1ff
	s_mov_b32 s89, s85
	v_lshrrev_b32_e32 v93, 16, v127
	v_lshrrev_b32_e32 v133, 16, v128
	v_add_u32_e32 v134, 0xfffffe01, v126
	v_mov_b32_e32 v143, 0
	v_mov_b32_e32 v102, 0xf149f2ca
	s_mov_b64 s[8:9], 0
	v_mov_b32_e32 v103, 0xf149f2ca
	v_mov_b32_e32 v56, 0
	v_add3_u32 v135, v51, v28, v29
	v_mov_b32_e32 v25, v24
	v_mov_b32_e32 v26, v24
	v_mov_b32_e32 v27, v24
	v_mov_b32_e32 v28, v24
	v_mov_b32_e32 v29, v24
	v_mov_b32_e32 v30, v24
	v_mov_b32_e32 v31, v24
	v_mov_b32_e32 v32, v24
	v_lshlrev_b32_e32 v96, 1, v34
	v_add_u32_e32 v137, v51, v41
	v_add3_u32 v138, v38, v39, v88
	v_add_u32_e32 v139, v51, v40
	v_lshl_add_u64 v[98:99], v[36:37], 0, s[4:5]
	s_cselect_b32 s0, s11, 0
	s_lshl_b32 s84, s12, 1
	v_mov_b32_e32 v34, v24
	v_mov_b32_e32 v36, v24
	v_mov_b32_e32 v37, v24
	v_mov_b32_e32 v38, v24
	v_mov_b32_e32 v39, v24
	v_mov_b32_e32 v40, v24
	v_mov_b32_e32 v41, v24
	v_mov_b32_e32 v42, v24
	v_mov_b32_e32 v43, v24
	v_mov_b32_e32 v44, v24
	v_mov_b32_e32 v45, v24
	v_mov_b32_e32 v46, v24
	v_mov_b32_e32 v47, v24
	v_mov_b32_e32 v48, v24
	v_mov_b32_e32 v49, v24
	v_mov_b32_e32 v50, v24
	v_mov_b32_e32 v51, v24
	v_mov_b32_e32 v52, v24
	v_mov_b32_e32 v53, v24
	v_mov_b32_e32 v54, v24
	v_mov_b32_e32 v55, v24
	v_mov_b32_e32 v100, v24
	v_mov_b32_e32 v101, v24
	s_waitcnt lgkmcnt(0)
	v_bitop3_b32 v140, v35, s10, v33 bitop3:0xc8
	v_mov_b32_e32 v33, v24
	v_mov_b32_e32 v35, v24
	v_mov_b32_e32 v176, 0
	v_mov_b32_e32 v177, 0
	v_mov_b32_e32 v178, v123
	v_mov_b32_e32 v179, v123
	s_mov_b32 s34, 0
	s_mov_b32 s35, 0
	v_lshl_add_u32 v183, v94, 1, v96
	v_readfirstlane_b32 s56, v98
	v_readfirstlane_b32 s57, v99
	v_readfirstlane_b32 s54, v140
	s_nop 1
	v_subrev_u32_e32 v163, s56, v98
	v_add_u32_e32 v216, 0x4800, v135
	v_add_u32_e32 v217, 0x5000, v135
	v_add_u32_e32 v218, 0x5800, v135
	v_add_u32_e32 v219, 0x6000, v135
	s_mov_b64 s[68:69], -1
	v_mov_b32_e32 v223, 0x5d800000
	s_branch .LBB0_618

; __device__ __forceinline__ f32x4 mfma16(bf16x8 a, bf16x8 b, f32x4 c) { return __builtin_amdgcn_mfma_f32_16x16x32_bf16(a, b, c, 0, 0, 0); }
; __device__ __forceinline__ void nsa_block_step(const bf16_t* Ks, const bf16_t* VT, const bf16x8 (&qf)[2][2], f32x4 (&O)[2][4], float (&m)[2], float (&l)[2],
;                                                int klo, int khi, int r, int q) {
;     f32x4 s[2][4];
; #pragma unroll
;     for (int x = 0; x < 2; x++)
; #pragma unroll
;         for (int kt = 0; kt < 4; kt++) s[x][kt] = (f32x4){0.f, 0.f, 0.f, 0.f};
; #pragma unroll
;     for (int kt = 0; kt < 4; kt++)
; #pragma unroll
;         for (int ks = 0; ks < 2; ks++) {
;             const bf16x8 kf = ld_frag(Ks + (kt * 16 + r) * 64 + (((ks * 4 + q) ^ (r & 7)) * 8));
; #pragma unroll
;             for (int x = 0; x < 2; x++) s[x][kt] = mfma16(kf, qf[x][ks], s[x][kt]);
;         }
;     if (!__all((klo <= 0) && (khi >= 63))) {
;         const int a = 4 * q - klo;
;         const unsigned range = (unsigned)(khi - klo);
;         const bool any = khi >= klo;
; #pragma unroll
;         for (int kt = 0; kt < 4; kt++)
; #pragma unroll
;             for (int j = 0; j < 4; j++) {
;                 const bool valid = any && ((unsigned)(kt * 16 + j + a) <= range);
; #pragma unroll
;                 for (int x = 0; x < 2; x++) s[x][kt][j] = valid ? s[x][kt][j] : -3.0e38f;
;             }
;     }
.Ln2_t_noload:
	s_barrier
	ds_read_b128 v[56:59], v137
	ds_read_b128 v[68:71], v139
	ds_read_b128 v[60:63], v137 offset:2048
	ds_read_b128 v[76:79], v139 offset:2048
	v_cmp_eq_u32_e32 vcc, 0, v97
	v_cmp_lt_i32_e64 s[6:7], 62, v88
	v_cmp_lt_i32_e64 s[48:49], v88, v97
	ds_read_b128 v[240:243], v137 offset:4096
	ds_read_b128 v[104:107], v139 offset:4096
	s_and_b64 s[6:7], vcc, s[6:7]
	s_or_b64 s[46:47], s[6:7], s[48:49]
	s_cmp_eq_u64 s[46:47], exec
	s_cselect_b64 s[48:49], s[48:49], 0
	s_andn2_b64 s[70:71], s[68:69], s[48:49]
	ds_read_b128 v[244:247], v137 offset:6144
	ds_read_b128 v[108:111], v139 offset:6144
	v_cndmask_b32_e64 v168, v176, v123, s[48:49]
	v_cndmask_b32_e64 v169, v176, v123, s[48:49]
	v_cndmask_b32_e64 v170, v176, v123, s[48:49]
	v_cndmask_b32_e64 v171, v176, v123, s[48:49]
	v_cndmask_b32_e64 v172, v177, v123, s[48:49]
	v_cndmask_b32_e64 v173, v177, v123, s[48:49]
	v_cndmask_b32_e64 v174, v177, v123, s[48:49]
	v_cndmask_b32_e64 v175, v177, v123, s[48:49]
	s_waitcnt lgkmcnt(7)
	v_mfma_f32_16x16x32_bf16 v[64:67], v[56:59], v[0:3], v[168:171]
	v_mfma_f32_16x16x32_bf16 v[56:59], v[56:59], v[8:11], v[172:175]
	s_waitcnt lgkmcnt(6)
	v_mfma_f32_16x16x32_bf16 v[80:83], v[68:71], v[4:7], v[64:67]
	v_mfma_f32_16x16x32_bf16 v[68:71], v[68:71], v[12:15], v[56:59]
	s_waitcnt lgkmcnt(5)
	v_mfma_f32_16x16x32_bf16 v[56:59], v[60:63], v[0:3], v[168:171]
	v_mfma_f32_16x16x32_bf16 v[60:63], v[60:63], v[8:11], v[172:175]
	s_waitcnt lgkmcnt(4)
	v_mfma_f32_16x16x32_bf16 v[72:75], v[76:79], v[4:7], v[56:59]
	v_mfma_f32_16x16x32_bf16 v[64:67], v[76:79], v[12:15], v[60:63]
	s_waitcnt lgkmcnt(3)
	v_mfma_f32_16x16x32_bf16 v[60:63], v[240:243], v[0:3], v[168:171]
	v_mfma_f32_16x16x32_bf16 v[56:59], v[240:243], v[8:11], v[172:175]
	s_waitcnt lgkmcnt(2)
	v_mfma_f32_16x16x32_bf16 v[84:87], v[104:107], v[4:7], v[60:63]
	v_mfma_f32_16x16x32_bf16 v[60:63], v[104:107], v[12:15], v[56:59]
	s_waitcnt lgkmcnt(1)
	v_mfma_f32_16x16x32_bf16 v[56:59], v[244:247], v[0:3], v[168:171]
	v_mfma_f32_16x16x32_bf16 v[104:107], v[244:247], v[8:11], v[172:175]
	s_waitcnt lgkmcnt(0)
	v_mfma_f32_16x16x32_bf16 v[76:79], v[108:111], v[4:7], v[56:59]
	v_mfma_f32_16x16x32_bf16 v[56:59], v[108:111], v[12:15], v[104:107]
	s_cmp_eq_u64 s[46:47], exec
	s_cbranch_scc1 .LBB0_628
	s_nop 1
	v_min_i32_e32 v88, 63, v88
	v_sub_u32_e32 v104, v88, v97
	v_cmp_ge_i32_e32 vcc, v88, v97
	v_sub_u32_e32 v88, v129, v97
	v_cmp_le_u32_e64 s[6:7], v88, v104
	s_and_b64 s[6:7], vcc, s[6:7]
	v_add_u32_e32 v97, 1, v88
	v_cndmask_b32_e64 v80, v123, v80, s[6:7]
	v_cndmask_b32_e64 v68, v123, v68, s[6:7]
	v_cmp_le_u32_e64 s[6:7], v97, v104
	s_and_b64 s[6:7], vcc, s[6:7]
	v_add_u32_e32 v97, 2, v88
	v_cndmask_b32_e64 v81, v123, v81, s[6:7]
	v_cndmask_b32_e64 v69, v123, v69, s[6:7]
	v_cmp_le_u32_e64 s[6:7], v97, v104
	s_and_b64 s[6:7], vcc, s[6:7]
	v_add_u32_e32 v97, 3, v88
	v_cndmask_b32_e64 v82, v123, v82, s[6:7]
	v_cndmask_b32_e64 v70, v123, v70, s[6:7]
	v_cmp_le_u32_e64 s[6:7], v97, v104
	s_and_b64 s[6:7], vcc, s[6:7]
	v_add_u32_e32 v97, 16, v88
	v_cndmask_b32_e64 v83, v123, v83, s[6:7]
	v_cndmask_b32_e64 v71, v123, v71, s[6:7]
	v_cmp_le_u32_e64 s[6:7], v97, v104
	s_and_b64 s[6:7], vcc, s[6:7]
	v_add_u32_e32 v97, 17, v88
	v_cndmask_b32_e64 v72, v123, v72, s[6:7]
	v_cndmask_b32_e64 v64, v123, v64, s[6:7]
	v_cmp_le_u32_e64 s[6:7], v97, v104
	s_and_b64 s[6:7], vcc, s[6:7]
	v_add_u32_e32 v97, 18, v88
	v_cndmask_b32_e64 v73, v123, v73, s[6:7]
	v_cndmask_b32_e64 v65, v123, v65, s[6:7]
	v_cmp_le_u32_e64 s[6:7], v97, v104
	s_and_b64 s[6:7], vcc, s[6:7]
	v_add_u32_e32 v97, 19, v88
	v_cndmask_b32_e64 v74, v123, v74, s[6:7]
	v_cndmask_b32_e64 v66, v123, v66, s[6:7]
	v_cmp_le_u32_e64 s[6:7], v97, v104
	s_and_b64 s[6:7], vcc, s[6:7]
	v_add_u32_e32 v97, 32, v88
	v_cndmask_b32_e64 v75, v123, v75, s[6:7]
	v_cndmask_b32_e64 v67, v123, v67, s[6:7]
	v_cmp_le_u32_e64 s[6:7], v97, v104
	s_and_b64 s[6:7], vcc, s[6:7]
	v_add_u32_e32 v97, 33, v88
	v_cndmask_b32_e64 v84, v123, v84, s[6:7]
	v_cndmask_b32_e64 v60, v123, v60, s[6:7]
	v_cmp_le_u32_e64 s[6:7], v97, v104
	s_and_b64 s[6:7], vcc, s[6:7]
	v_add_u32_e32 v97, 34, v88
	v_cndmask_b32_e64 v85, v123, v85, s[6:7]
	v_cndmask_b32_e64 v61, v123, v61, s[6:7]
	v_cmp_le_u32_e64 s[6:7], v97, v104
	s_and_b64 s[6:7], vcc, s[6:7]
	v_add_u32_e32 v97, 35, v88
	v_cndmask_b32_e64 v86, v123, v86, s[6:7]
	v_cndmask_b32_e64 v62, v123, v62, s[6:7]
	v_cmp_le_u32_e64 s[6:7], v97, v104
	s_and_b64 s[6:7], vcc, s[6:7]
	v_add_u32_e32 v97, 48, v88
	v_cndmask_b32_e64 v87, v123, v87, s[6:7]
	v_cndmask_b32_e64 v63, v123, v63, s[6:7]
	v_cmp_le_u32_e64 s[6:7], v97, v104
	s_and_b64 s[6:7], vcc, s[6:7]
	v_add_u32_e32 v97, 49, v88
	v_cndmask_b32_e64 v76, v123, v76, s[6:7]
	v_cndmask_b32_e64 v56, v123, v56, s[6:7]
	v_cmp_le_u32_e64 s[6:7], v97, v104
	s_and_b64 s[6:7], vcc, s[6:7]
	v_add_u32_e32 v97, 50, v88
	v_cndmask_b32_e64 v77, v123, v77, s[6:7]
	v_cndmask_b32_e64 v57, v123, v57, s[6:7]
	v_cmp_le_u32_e64 s[6:7], v97, v104
	s_and_b64 s[6:7], vcc, s[6:7]
	v_add_u32_e32 v88, 51, v88
	v_cndmask_b32_e64 v78, v123, v78, s[6:7]
	v_cndmask_b32_e64 v58, v123, v58, s[6:7]
	v_cmp_le_u32_e64 s[6:7], v88, v104
	s_and_b64 vcc, vcc, s[6:7]
	v_cndmask_b32_e32 v79, v123, v79, vcc
	v_cndmask_b32_e32 v59, v123, v59, vcc
.LBB0_628:
	s_cmp_lg_u64 s[70:71], 0
	s_cbranch_scc0 .Ln2_fast
; __device__ __forceinline__ float exp2f_(float x) { return __builtin_amdgcn_exp2f(x); }
; __device__ __forceinline__ void nsa_block_step(const bf16_t* Ks, const bf16_t* VT, const bf16x8 (&qf)[2][2], f32x4 (&O)[2][4], float (&m)[2], float (&l)[2],
;                                                int klo, int khi, int r, int q) {
;     ...
;     bf16x8 pbv[2][2];
; #pragma unroll
;     for (int x = 0; x < 2; x++) {
;         float mx = fmaxf(fmaxf(fmaxf(s[x][0][0], s[x][0][1]), fmaxf(s[x][0][2], s[x][0][3])), fmaxf(fmaxf(s[x][1][0], s[x][1][1]), fmaxf(s[x][1][2], s[x][1][3])));
;         mx = fmaxf(mx, fmaxf(fmaxf(fmaxf(s[x][2][0], s[x][2][1]), fmaxf(s[x][2][2], s[x][2][3])), fmaxf(fmaxf(s[x][3][0], s[x][3][1]), fmaxf(s[x][3][2], s[x][3][3]))));
;         mx = xrow_max(mx);
;         const float mnew = fmaxf(m[x], mx);
;         const float alpha = exp2f_(m[x] - mnew);
;         m[x] = mnew;
;         float ls = 0.f;
; #pragma unroll
;         for (int kt = 0; kt < 4; kt++)
; #pragma unroll
;             for (int j = 0; j < 4; j++) { const float pv = exp2f_(s[x][kt][j] - mnew); s[x][kt][j] = pv; ls += pv; }
;         l[x] = l[x] * alpha + ls;
; #pragma unroll
;         for (int dt = 0; dt < 4; dt++) O[x][dt] *= alpha;
.Ln2_slow:
	v_max3_f32 v88, v80, v81, v82
	v_max3_f32 v164, v68, v69, v70
	v_max3_f32 v97, v72, v73, v74
	v_max3_f32 v165, v64, v65, v66
	v_max3_f32 v104, v84, v85, v86
	v_max3_f32 v166, v60, v61, v62
	v_max3_f32 v105, v76, v77, v78
	v_max3_f32 v167, v56, v57, v58
	v_max3_f32 v88, v88, v83, v75
	v_max3_f32 v164, v164, v71, v67
	v_max3_f32 v97, v97, v87, v79
	v_max3_f32 v165, v165, v63, v59
	v_max3_f32 v88, v88, v97, v104
	v_max3_f32 v164, v164, v165, v166
	v_max_f32_e32 v88, v88, v105
	v_max_f32_e32 v164, v164, v167
	v_add_f32_e32 v180, v103, v176
	v_add_f32_e32 v182, v102, v177
	v_mov_b32_e32 v97, v88
	v_mov_b32_e32 v165, v164
	s_nop 0
	v_permlane16_swap_b32_e32 v88, v97
	s_nop 0
	v_permlane16_swap_b32_e32 v164, v165
	v_max_f32_e32 v88, v88, v97
	v_max_f32_e32 v164, v164, v165
	v_mov_b32_e32 v97, v88
	v_mov_b32_e32 v165, v164
	s_nop 0
	v_permlane32_swap_b32_e32 v88, v97
	s_nop 0
	v_permlane32_swap_b32_e32 v164, v165
	v_max3_f32 v88, v180, v88, v97
	v_sub_f32_e32 v72, v72, v88
	v_exp_f32_e32 v105, v72
	v_sub_f32_e32 v72, v73, v88
	v_exp_f32_e32 v109, v72
	v_sub_f32_e32 v72, v74, v88
	v_exp_f32_e32 v107, v72
	v_sub_f32_e32 v72, v75, v88
	v_sub_f32_e32 v80, v80, v88
	v_exp_f32_e32 v111, v72
	v_sub_f32_e32 v72, v84, v88
	v_exp_f32_e32 v117, v80
	v_sub_f32_e32 v80, v81, v88
	v_exp_f32_e32 v73, v72
	v_sub_f32_e32 v72, v85, v88
	v_exp_f32_e32 v113, v80
	v_sub_f32_e32 v80, v82, v88
	v_exp_f32_e32 v75, v72
	v_sub_f32_e32 v72, v86, v88
	v_exp_f32_e32 v115, v80
	v_sub_f32_e32 v80, v83, v88
	v_exp_f32_e32 v83, v72
	v_sub_f32_e32 v72, v87, v88
	v_exp_f32_e32 v81, v72
	v_sub_f32_e32 v72, v76, v88
	v_exp_f32_e32 v85, v72
	v_sub_f32_e32 v72, v77, v88
	v_exp_f32_e32 v87, v72
	v_sub_f32_e32 v72, v78, v88
	v_exp_f32_e32 v77, v72
	v_sub_f32_e32 v72, v79, v88
	v_exp_f32_e32 v79, v72
	v_sub_f32_e32 v97, v180, v88
	v_exp_f32_e32 v103, v80
	v_exp_f32_e32 v76, v97
	v_max3_f32 v97, v182, v164, v165
	v_sub_f32_e32 v64, v64, v97
	v_sub_f32_e32 v68, v68, v97
	v_exp_f32_e32 v104, v64
	v_sub_f32_e32 v64, v65, v97
	v_sub_f32_e32 v78, v182, v97
	v_exp_f32_e32 v116, v68
	v_sub_f32_e32 v68, v69, v97
	v_exp_f32_e32 v108, v64
	v_sub_f32_e32 v64, v66, v97
	v_exp_f32_e32 v112, v68
	v_exp_f32_e32 v106, v64
	v_sub_f32_e32 v64, v67, v97
	v_sub_f32_e32 v60, v60, v97
	v_exp_f32_e32 v160, v78
	v_add_u32_e32 v78, 0x4800, v135
	v_exp_f32_e32 v110, v64
	v_exp_f32_e32 v72, v60
	v_sub_f32_e32 v60, v61, v97
	ds_read2_b64 v[64:67], v78 offset1:4
	v_exp_f32_e32 v74, v60
	v_sub_f32_e32 v60, v62, v97
	v_sub_f32_e32 v68, v70, v97
	v_exp_f32_e32 v82, v60
	v_sub_f32_e32 v60, v63, v97
	v_exp_f32_e32 v114, v68
	v_sub_f32_e32 v68, v71, v97
	v_pk_add_f32 v[156:157], v[116:117], 0 op_sel_hi:[1,0]
	v_exp_f32_e32 v80, v60
	v_cvt_pk_bf16_f32 v60, v116, v112
	v_add_u32_e32 v116, 0x5000, v135
	v_exp_f32_e32 v102, v68
	ds_read2_b64 v[68:71], v116 offset0:32 offset1:36
	v_mov_b32_e32 v161, v76
	v_pk_mul_f32 v[146:147], v[54:55], v[76:77] op_sel_hi:[1,0]
	v_pk_mul_f32 v[144:145], v[52:53], v[76:77] op_sel_hi:[1,0]
	v_cvt_pk_bf16_f32 v52, v117, v113
	v_cvt_pk_bf16_f32 v53, v115, v103
	v_cvt_pk_bf16_f32 v54, v105, v109
	v_cvt_pk_bf16_f32 v55, v107, v111
	v_pk_mul_f32 v[38:39], v[38:39], v[160:161] op_sel_hi:[1,0]
	v_pk_mul_f32 v[36:37], v[36:37], v[160:161] op_sel_hi:[1,0]
	v_cvt_pk_bf16_f32 v61, v114, v102
	v_cvt_pk_bf16_f32 v62, v104, v108
	v_cvt_pk_bf16_f32 v63, v106, v110
	v_add_u32_e32 v117, 0x5800, v135
	s_waitcnt lgkmcnt(1)
	v_mfma_f32_16x16x32_bf16 v[144:147], v[64:67], v[52:55], v[144:147]
	v_mul_f32_e64 v150, v50, v76
	v_mul_f32_e64 v151, v51, v76
	v_pk_mul_f32 v[148:149], v[48:49], v[76:77] op_sel_hi:[1,0]
	v_pk_mul_f32 v[34:35], v[34:35], v[160:161] op_sel_hi:[1,0]
	v_mfma_f32_16x16x32_bf16 v[36:39], v[64:67], v[60:63], v[36:39]
	ds_read2_b64 v[64:67], v117 offset0:64 offset1:68
	v_pk_mul_f32 v[32:33], v[32:33], v[160:161] op_sel_hi:[1,0]
	v_add_u32_e32 v162, 0x6000, v135
	s_waitcnt lgkmcnt(1)
	v_mfma_f32_16x16x32_bf16 v[148:151], v[68:71], v[52:55], v[148:151]
	v_mul_f32_e64 v50, v46, v76
	v_mul_f32_e64 v51, v47, v76
	v_pk_mul_f32 v[48:49], v[44:45], v[76:77] op_sel_hi:[1,0]
	v_pk_mul_f32 v[46:47], v[42:43], v[76:77] op_sel_hi:[1,0]
	v_mfma_f32_16x16x32_bf16 v[32:35], v[68:71], v[60:63], v[32:35]
	ds_read2_b64 v[68:71], v162 offset0:96 offset1:100
	v_pk_mul_f32 v[44:45], v[40:41], v[76:77] op_sel_hi:[1,0]
	v_sub_f32_e32 v56, v56, v97
	s_waitcnt lgkmcnt(1)
	v_mfma_f32_16x16x32_bf16 v[152:155], v[64:67], v[52:55], v[48:51]
	v_mul_f32_e64 v30, v30, v160
	v_mul_f32_e64 v31, v31, v160
	v_pk_mul_f32 v[28:29], v[28:29], v[160:161] op_sel_hi:[1,0]
	v_exp_f32_e32 v84, v56
	v_sub_f32_e32 v48, v58, v97
	v_exp_f32_e32 v76, v48
	ds_read2_b64 v[48:51], v78 offset0:8 offset1:12
	v_sub_f32_e32 v56, v57, v97
	v_mfma_f32_16x16x32_bf16 v[28:31], v[64:67], v[60:63], v[28:31]
	v_exp_f32_e32 v86, v56
	v_cvt_pk_bf16_f32 v40, v73, v75
	v_cvt_pk_bf16_f32 v41, v83, v81
	s_waitcnt lgkmcnt(1)
	v_mfma_f32_16x16x32_bf16 v[64:67], v[68:71], v[52:55], v[44:47]
	v_cvt_pk_bf16_f32 v42, v85, v87
	v_cvt_pk_bf16_f32 v43, v77, v79
	v_cvt_pk_bf16_f32 v56, v72, v74
	v_sub_f32_e32 v44, v59, v97
	v_exp_f32_e32 v78, v44
	ds_read2_b64 v[44:47], v116 offset0:40 offset1:44
	v_cvt_pk_bf16_f32 v57, v82, v80
	v_cvt_pk_bf16_f32 v58, v84, v86
	v_cvt_pk_bf16_f32 v59, v76, v78
	v_pk_mul_f32 v[26:27], v[26:27], v[160:161] op_sel_hi:[1,0]
	v_pk_mul_f32 v[24:25], v[24:25], v[160:161] op_sel_hi:[1,0]
	s_waitcnt lgkmcnt(1)
; __device__ __forceinline__ float sigmoidf_(float x) { return __builtin_amdgcn_rcpf(1.f + __expf(-x)); }
; __device__ __forceinline__ f32x4 mfma16(bf16x8 a, bf16x8 b, f32x4 c) { return __builtin_amdgcn_mfma_f32_16x16x32_bf16(a, b, c, 0, 0, 0); }
; __device__ __forceinline__ void nsa_block_step(const bf16_t* Ks, const bf16_t* VT, const bf16x8 (&qf)[2][2], f32x4 (&O)[2][4], float (&m)[2], float (&l)[2],
;                                                int klo, int khi, int r, int q) {
;     ...
;         l[x] = l[x] * alpha + ls;
; #pragma unroll
;         for (int dt = 0; dt < 4; dt++) O[x][dt] *= alpha;
; #pragma unroll
;         for (int s2 = 0; s2 < 2; s2++) {
;             const u32x4 t4 = {pack2(s[x][2 * s2][0], s[x][2 * s2][1]), pack2(s[x][2 * s2][2], s[x][2 * s2][3]),
;                               pack2(s[x][2 * s2 + 1][0], s[x][2 * s2 + 1][1]), pack2(s[x][2 * s2 + 1][2], s[x][2 * s2 + 1][3])};
;             pbv[x][s2] = __builtin_bit_cast(bf16x8, t4);
;         }
;     }
; #pragma unroll
;     for (int s2 = 0; s2 < 2; s2++)
; #pragma unroll
;         for (int dt = 0; dt < 4; dt++) {
;             const u32x2 lo = *(const u32x2*)(VT + (dt * 16 + r) * 72 + (2 * s2) * 16 + 4 * q);
;             const u32x2 hi = *(const u32x2*)(VT + (dt * 16 + r) * 72 + (2 * s2 + 1) * 16 + 4 * q);
;             const bf16x8 va = mk_frag(lo, hi);
; #pragma unroll
;             for (int x = 0; x < 2; x++) O[x][dt] = mfma16(va, pbv[x][s2], O[x][dt]);
;         }
; __device__ void phaseN2_task(const Params& p, int task, char* lds, bf16_t* ydst, int ystride, volatile unsigned* uex, char* ldsb) {
;     ...
;             if (nbr != br) {
; #pragma unroll
;                 for (int x = 0; x < 2; x++) {
;                     float lt = l[x];
;                     lt = xrow_sum(lt);
;                     const float sc = sigmoidf_(br == 0 ? gatev[1][x] : gatev[2][x]) / lt;
; #pragma unroll
;                     for (int dt = 0; dt < 4; dt++) { ofl[(wave * 8 + x * 4 + dt) * 64 + lane] += sc * O[x][dt]; O[x][dt] = (f32x4){0.f, 0.f, 0.f, 0.f}; }
;                     m[x] = -1e30f; l[x] = 0.f;
;                 }
;             }
	v_mfma_f32_16x16x32_bf16 v[52:55], v[48:51], v[40:43], v[144:147]
	v_cmp_ne_u32_e32 vcc, v141, v143
	v_mfma_f32_16x16x32_bf16 v[36:39], v[48:51], v[56:59], v[36:39]
	v_add_f32_e64 v48, v112, v156
	v_add_f32_e64 v49, v113, v157
	v_mfma_f32_16x16x32_bf16 v[24:27], v[68:71], v[60:63], v[24:27]
	v_add_f32_e64 v68, v114, v48
	v_add_f32_e64 v69, v115, v49
	ds_read2_b64 v[60:63], v117 offset0:72 offset1:76
	v_pk_add_f32 v[68:69], v[102:103], v[68:69]
	s_waitcnt lgkmcnt(1)
	v_mfma_f32_16x16x32_bf16 v[48:51], v[44:47], v[40:43], v[148:151]
	v_add_f32_e64 v68, v104, v68
	v_add_f32_e64 v69, v105, v69
	v_pk_add_f32 v[68:69], v[108:109], v[68:69]
	v_mfma_f32_16x16x32_bf16 v[32:35], v[44:47], v[56:59], v[32:35]
	v_add_f32_e64 v44, v106, v68
	v_add_f32_e64 v45, v107, v69
	ds_read2_b64 v[68:71], v162 offset0:104 offset1:108
	v_pk_add_f32 v[102:103], v[110:111], v[44:45]
	s_waitcnt lgkmcnt(1)
	v_mfma_f32_16x16x32_bf16 v[44:47], v[60:63], v[40:43], v[152:155]
	v_add_f32_e64 v72, v72, v102
	v_add_f32_e64 v73, v73, v103
	v_pk_add_f32 v[72:73], v[74:75], v[72:73]
	v_mfma_f32_16x16x32_bf16 v[28:31], v[60:63], v[56:59], v[28:31]
	v_add_f32_e64 v72, v82, v72
	v_add_f32_e64 v73, v83, v73
	v_pk_add_f32 v[60:61], v[80:81], v[72:73]
	s_waitcnt lgkmcnt(0)
	v_mfma_f32_16x16x32_bf16 v[40:43], v[68:71], v[40:43], v[64:67]
	v_add_f32_e64 v60, v84, v60
	v_add_f32_e64 v61, v85, v61
	v_pk_add_f32 v[60:61], v[86:87], v[60:61]
	v_mfma_f32_16x16x32_bf16 v[24:27], v[68:71], v[56:59], v[24:27]
	v_add_f32_e64 v60, v76, v60
	v_add_f32_e64 v61, v77, v61
	v_pk_add_f32 v[60:61], v[78:79], v[60:61]
	s_nop 0
	v_pk_fma_f32 v[100:101], v[100:101], v[160:161], v[60:61]
	s_mov_b32 s45, 0xf0a18f08
	v_sub_f32_e32 v88, v88, v176
	v_sub_f32_e32 v97, v97, v177
	v_cmp_lt_f32_e64 s[46:47], v88, s45
	v_cmp_lt_f32_e64 s[48:49], v97, s45
	s_or_b64 s[68:69], s[46:47], s[48:49]
	v_sub_f32_e32 v176, 0, v88
	v_sub_f32_e32 v177, 0, v97
	v_cndmask_b32_e64 v176, v176, 0, s[46:47]
	v_cndmask_b32_e64 v177, v177, 0, s[48:49]
	v_cndmask_b32_e64 v178, 4.0, v123, s[46:47]
	v_cndmask_b32_e64 v179, 4.0, v123, s[48:49]
.Ln2_tail:
	s_and_saveexec_b64 s[6:7], vcc
	s_cbranch_execz .LBB0_617
	s_mov_b64 vcc, s[4:5]
	v_cndmask_b32_sdwa v57, v128, v127, vcc dst_sel:WORD_1 dst_unused:UNUSED_PAD src0_sel:DWORD src1_sel:DWORD
	v_mov_b32_e32 v56, v101
	v_mul_f32_e32 v57, 0xbfb8aa3b, v57
	v_exp_f32_e32 v57, v57
	v_permlane16_swap_b32_e32 v101, v56
	v_add_f32_e32 v56, v101, v56
	v_add_f32_e32 v57, 1.0, v57
	v_rcp_f32_e32 v60, v57
	v_mov_b32_e32 v58, v56
	s_nop 1
	v_permlane32_swap_b32_e32 v56, v58
	v_add_f32_e32 v61, v56, v58
	v_div_scale_f32 v56, s[10:11], v61, v61, v60
	v_rcp_f32_e32 v62, v56
	v_mov_b32_e32 v97, 0xf149f2ca
	v_mov_b32_e32 v88, 0xf149f2ca
	s_mov_b64 s[68:69], -1
	v_mov_b32_e32 v176, 0
	v_mov_b32_e32 v177, 0
	v_mov_b32_e32 v178, v123
	v_mov_b32_e32 v179, v123
	v_fma_f32 v57, -v56, v62, 1.0
	v_fmac_f32_e32 v62, v57, v62
	v_div_scale_f32 v57, vcc, v60, v61, v60
	v_mul_f32_e32 v63, v57, v62
	v_fma_f32 v58, -v56, v63, v57
	v_fmac_f32_e32 v63, v58, v62
	v_fma_f32 v64, -v56, v63, v57
	ds_read_b128 v[56:59], v131 offset:35840
	v_div_fmas_f32 v62, v64, v62, v63
	v_div_fixup_f32 v64, v62, v61, v60
	ds_read_b128 v[60:63], v131 offset:36864
	s_waitcnt lgkmcnt(1)
	v_pk_fma_f32 v[54:55], v[54:55], v[64:65], v[58:59] op_sel_hi:[1,0,1]
	v_pk_fma_f32 v[52:53], v[52:53], v[64:65], v[56:57] op_sel_hi:[1,0,1]
	ds_write_b128 v131, v[52:55] offset:35840
	ds_read_b128 v[52:55], v131 offset:37888
	s_waitcnt lgkmcnt(2)
	v_pk_fma_f32 v[50:51], v[50:51], v[64:65], v[62:63] op_sel_hi:[1,0,1]
	v_pk_fma_f32 v[48:49], v[48:49], v[64:65], v[60:61] op_sel_hi:[1,0,1]
	ds_write_b128 v131, v[48:51] offset:36864
	ds_read_b128 v[48:51], v131 offset:38912
	s_waitcnt lgkmcnt(2)
	v_pk_fma_f32 v[46:47], v[46:47], v[64:65], v[54:55] op_sel_hi:[1,0,1]
	v_pk_fma_f32 v[44:45], v[44:45], v[64:65], v[52:53] op_sel_hi:[1,0,1]
	ds_write_b128 v131, v[44:47] offset:37888
	v_cndmask_b32_e64 v45, v133, v93, s[4:5]
	v_lshlrev_b32_e32 v45, 16, v45
	v_mul_f32_e32 v45, 0xbfb8aa3b, v45
	v_exp_f32_e32 v45, v45
	v_mov_b32_e32 v44, v100
	s_nop 1
	v_permlane16_swap_b32_e32 v100, v44
	v_add_f32_e32 v45, 1.0, v45
	v_add_f32_e32 v44, v100, v44
	v_rcp_f32_e32 v45, v45
	v_mov_b32_e32 v46, v44
	s_nop 1
	v_permlane32_swap_b32_e32 v44, v46
	v_add_f32_e32 v44, v44, v46
	v_div_scale_f32 v46, s[4:5], v44, v44, v45
	v_rcp_f32_e32 v47, v46
	s_waitcnt lgkmcnt(1)
	v_pk_fma_f32 v[42:43], v[42:43], v[64:65], v[50:51] op_sel_hi:[1,0,1]
	v_pk_fma_f32 v[40:41], v[40:41], v[64:65], v[48:49] op_sel_hi:[1,0,1]
	ds_write_b128 v131, v[40:43] offset:38912
	v_fma_f32 v40, -v46, v47, 1.0
	v_fmac_f32_e32 v47, v40, v47
	v_div_scale_f32 v40, vcc, v45, v44, v45
	v_mul_f32_e32 v48, v40, v47
	v_fma_f32 v41, -v46, v48, v40
	v_fmac_f32_e32 v48, v41, v47
	v_fma_f32 v46, -v46, v48, v40
	ds_read_b128 v[40:43], v131 offset:39936
	v_div_fmas_f32 v46, v46, v47, v48
	v_div_fixup_f32 v48, v46, v44, v45
	ds_read_b128 v[44:47], v131 offset:40960
	s_waitcnt lgkmcnt(1)
	v_pk_fma_f32 v[38:39], v[38:39], v[48:49], v[42:43] op_sel_hi:[1,0,1]
	v_pk_fma_f32 v[36:37], v[36:37], v[48:49], v[40:41] op_sel_hi:[1,0,1]
	ds_write_b128 v131, v[36:39] offset:39936
	ds_read_b128 v[36:39], v131 offset:41984
	ds_read_b128 v[40:43], v131 offset:43008
	s_waitcnt lgkmcnt(3)
	v_pk_fma_f32 v[34:35], v[34:35], v[48:49], v[46:47] op_sel_hi:[1,0,1]
	v_pk_fma_f32 v[32:33], v[32:33], v[48:49], v[44:45] op_sel_hi:[1,0,1]
	ds_write_b128 v131, v[32:35] offset:40960
	s_waitcnt lgkmcnt(2)
	v_pk_fma_f32 v[30:31], v[30:31], v[48:49], v[38:39] op_sel_hi:[1,0,1]
	s_waitcnt lgkmcnt(1)
	v_pk_fma_f32 v[26:27], v[26:27], v[48:49], v[42:43] op_sel_hi:[1,0,1]
	v_pk_fma_f32 v[24:25], v[24:25], v[48:49], v[40:41] op_sel_hi:[1,0,1]
	v_pk_fma_f32 v[28:29], v[28:29], v[48:49], v[36:37] op_sel_hi:[1,0,1]
	ds_write_b128 v131, v[24:27] offset:43008
	v_mov_b32_e32 v24, 0
	ds_write_b128 v131, v[28:31] offset:41984
	v_mov_b32_e32 v25, v24
	v_mov_b32_e32 v26, v24
	v_mov_b32_e32 v27, v24
	v_mov_b32_e32 v28, v24
	v_mov_b32_e32 v29, v24
	v_mov_b32_e32 v30, v24
	v_mov_b32_e32 v31, v24
	v_mov_b32_e32 v32, v24
	v_mov_b32_e32 v33, v24
	v_mov_b32_e32 v34, v24
	v_mov_b32_e32 v35, v24
	v_mov_b32_e32 v36, v24
	v_mov_b32_e32 v37, v24
	v_mov_b32_e32 v38, v24
	v_mov_b32_e32 v39, v24
	v_mov_b32_e32 v40, v24
	v_mov_b32_e32 v41, v24
	v_mov_b32_e32 v42, v24
	v_mov_b32_e32 v43, v24
	v_mov_b32_e32 v44, v24
	v_mov_b32_e32 v45, v24
	v_mov_b32_e32 v46, v24
	v_mov_b32_e32 v47, v24
	v_mov_b32_e32 v48, v24
	v_mov_b32_e32 v49, v24
	v_mov_b32_e32 v50, v24
	v_mov_b32_e32 v51, v24
	v_mov_b32_e32 v52, v24
	v_mov_b32_e32 v53, v24
	v_mov_b32_e32 v54, v24
	v_mov_b32_e32 v55, v24
	v_mov_b32_e32 v100, v24
	v_mov_b32_e32 v101, v24
	s_branch .LBB0_617
; __device__ __forceinline__ float exp2f_(float x) { return __builtin_amdgcn_exp2f(x); }
; __device__ __forceinline__ f32x4 mfma16(bf16x8 a, bf16x8 b, f32x4 c) { return __builtin_amdgcn_mfma_f32_16x16x32_bf16(a, b, c, 0, 0, 0); }
; __device__ __forceinline__ void nsa_block_step(const bf16_t* Ks, const bf16_t* VT, const bf16x8 (&qf)[2][2], f32x4 (&O)[2][4], float (&m)[2], float (&l)[2],
;                                                int klo, int khi, int r, int q) {
;     ...
;     bf16x8 pbv[2][2];
; #pragma unroll
;     for (int x = 0; x < 2; x++) {
;         float mx = fmaxf(fmaxf(fmaxf(s[x][0][0], s[x][0][1]), fmaxf(s[x][0][2], s[x][0][3])), fmaxf(fmaxf(s[x][1][0], s[x][1][1]), fmaxf(s[x][1][2], s[x][1][3])));
;         mx = fmaxf(mx, fmaxf(fmaxf(fmaxf(s[x][2][0], s[x][2][1]), fmaxf(s[x][2][2], s[x][2][3])), fmaxf(fmaxf(s[x][3][0], s[x][3][1]), fmaxf(s[x][3][2], s[x][3][3]))));
;         mx = xrow_max(mx);
;         const float mnew = fmaxf(m[x], mx);
;         const float alpha = exp2f_(m[x] - mnew);
;         m[x] = mnew;
;         float ls = 0.f;
; #pragma unroll
;         for (int kt = 0; kt < 4; kt++)
; #pragma unroll
;             for (int j = 0; j < 4; j++) { const float pv = exp2f_(s[x][kt][j] - mnew); s[x][kt][j] = pv; ls += pv; }
;         l[x] = l[x] * alpha + ls;
; #pragma unroll
;         for (int dt = 0; dt < 4; dt++) O[x][dt] *= alpha;
; #pragma unroll
;         for (int s2 = 0; s2 < 2; s2++) {
;             const u32x4 t4 = {pack2(s[x][2 * s2][0], s[x][2 * s2][1]), pack2(s[x][2 * s2][2], s[x][2 * s2][3]),
;                               pack2(s[x][2 * s2 + 1][0], s[x][2 * s2 + 1][1]), pack2(s[x][2 * s2 + 1][2], s[x][2 * s2 + 1][3])};
;             pbv[x][s2] = __builtin_bit_cast(bf16x8, t4);
;         }
;     }
; #pragma unroll
;     for (int s2 = 0; s2 < 2; s2++)
; #pragma unroll
;         for (int dt = 0; dt < 4; dt++) {
;             const u32x2 lo = *(const u32x2*)(VT + (dt * 16 + r) * 72 + (2 * s2) * 16 + 4 * q);
;             const u32x2 hi = *(const u32x2*)(VT + (dt * 16 + r) * 72 + (2 * s2 + 1) * 16 + 4 * q);
;             const bf16x8 va = mk_frag(lo, hi);
; #pragma unroll
;             for (int x = 0; x < 2; x++) O[x][dt] = mfma16(va, pbv[x][s2], O[x][dt]);
;         }
.Ln2_fast:
	ds_read2_b64 v[200:203], v216 offset1:4
	ds_read2_b64 v[204:207], v217 offset0:32 offset1:36
	ds_read2_b64 v[208:211], v218 offset0:64 offset1:68
	ds_read2_b64 v[212:215], v219 offset0:96 offset1:100
	v_exp_f32_e32 v104, v80
	v_exp_f32_e32 v105, v81
	v_exp_f32_e32 v106, v82
	v_exp_f32_e32 v107, v83
	v_exp_f32_e32 v144, v68
	v_exp_f32_e32 v145, v69
	v_exp_f32_e32 v146, v70
	v_exp_f32_e32 v147, v71
	ds_read2_b64 v[224:227], v216 offset0:8 offset1:12
	ds_read2_b64 v[228:231], v217 offset0:40 offset1:44
	v_exp_f32_e32 v108, v72
	v_exp_f32_e32 v109, v73
	v_exp_f32_e32 v110, v74
	v_exp_f32_e32 v111, v75
	v_exp_f32_e32 v148, v64
	v_exp_f32_e32 v149, v65
	v_exp_f32_e32 v150, v66
	v_exp_f32_e32 v151, v67
	ds_read2_b64 v[232:235], v218 offset0:72 offset1:76
	ds_read2_b64 v[236:239], v219 offset0:104 offset1:108
	v_exp_f32_e32 v112, v84
	v_exp_f32_e32 v113, v85
	v_exp_f32_e32 v114, v86
	v_exp_f32_e32 v115, v87
	v_exp_f32_e32 v152, v60
	v_exp_f32_e32 v153, v61
	v_exp_f32_e32 v154, v62
	v_exp_f32_e32 v155, v63
	v_exp_f32_e32 v116, v76
	v_exp_f32_e32 v117, v77
	v_exp_f32_e32 v248, v78
	v_exp_f32_e32 v249, v79
	v_exp_f32_e32 v156, v56
	v_exp_f32_e32 v157, v57
	v_exp_f32_e32 v250, v58
	v_exp_f32_e32 v251, v59
	v_add_f32_e32 v221, v104, v105
	v_add_f32_e32 v220, v144, v145
	v_add_f32_e32 v221, v221, v106
	v_add_f32_e32 v220, v220, v146
	v_add_f32_e32 v221, v221, v107
	v_add_f32_e32 v220, v220, v147
	v_add_f32_e32 v221, v221, v108
	v_add_f32_e32 v220, v220, v148
	v_add_f32_e32 v221, v221, v109
	v_add_f32_e32 v220, v220, v149
	v_add_f32_e32 v221, v221, v110
	v_add_f32_e32 v220, v220, v150
	v_add_f32_e32 v221, v221, v111
	v_add_f32_e32 v220, v220, v151
	v_add_f32_e32 v221, v221, v112
	v_add_f32_e32 v220, v220, v152
	v_add_f32_e32 v221, v221, v113
	v_add_f32_e32 v220, v220, v153
	v_add_f32_e32 v221, v221, v114
	v_add_f32_e32 v220, v220, v154
	v_add_f32_e32 v221, v221, v115
	v_add_f32_e32 v220, v220, v155
	v_add_f32_e32 v221, v221, v116
	v_add_f32_e32 v220, v220, v156
	v_add_f32_e32 v221, v221, v117
	v_add_f32_e32 v220, v220, v157
	v_add_f32_e32 v221, v221, v248
	v_add_f32_e32 v220, v220, v250
	v_add_f32_e32 v221, v221, v249
	v_add_f32_e32 v220, v220, v251
	v_cmp_gt_f32_e32 vcc, v221, v223
	v_cmp_gt_f32_e64 s[46:47], v220, v223
	s_or_b64 vcc, vcc, s[46:47]
	s_cbranch_vccnz .Ln2_slow
	v_cvt_pk_bf16_f32 v184, v104, v105
	v_cvt_pk_bf16_f32 v185, v106, v107
	v_cvt_pk_bf16_f32 v186, v108, v109
	v_cvt_pk_bf16_f32 v187, v110, v111
	v_cvt_pk_bf16_f32 v192, v144, v145
	v_cvt_pk_bf16_f32 v193, v146, v147
	v_cvt_pk_bf16_f32 v194, v148, v149
	v_cvt_pk_bf16_f32 v195, v150, v151
	v_cvt_pk_bf16_f32 v188, v112, v113
	v_cvt_pk_bf16_f32 v189, v114, v115
	v_cvt_pk_bf16_f32 v190, v116, v117
	v_cvt_pk_bf16_f32 v191, v248, v249
	v_cvt_pk_bf16_f32 v196, v152, v153
	v_cvt_pk_bf16_f32 v197, v154, v155
	v_cvt_pk_bf16_f32 v198, v156, v157
	v_cvt_pk_bf16_f32 v199, v250, v251
	s_waitcnt lgkmcnt(7)
	v_mfma_f32_16x16x32_bf16 v[52:55], v[200:203], v[184:187], v[52:55]
	v_mfma_f32_16x16x32_bf16 v[36:39], v[200:203], v[192:195], v[36:39]
	s_waitcnt lgkmcnt(6)
	v_mfma_f32_16x16x32_bf16 v[48:51], v[204:207], v[184:187], v[48:51]
	v_mfma_f32_16x16x32_bf16 v[32:35], v[204:207], v[192:195], v[32:35]
	s_waitcnt lgkmcnt(5)
	v_mfma_f32_16x16x32_bf16 v[44:47], v[208:211], v[184:187], v[44:47]
	v_mfma_f32_16x16x32_bf16 v[28:31], v[208:211], v[192:195], v[28:31]
	s_waitcnt lgkmcnt(4)
	v_mfma_f32_16x16x32_bf16 v[40:43], v[212:215], v[184:187], v[40:43]
	v_mfma_f32_16x16x32_bf16 v[24:27], v[212:215], v[192:195], v[24:27]
	s_waitcnt lgkmcnt(3)
	v_mfma_f32_16x16x32_bf16 v[52:55], v[224:227], v[188:191], v[52:55]
	v_mfma_f32_16x16x32_bf16 v[36:39], v[224:227], v[196:199], v[36:39]
	s_waitcnt lgkmcnt(2)
	v_mfma_f32_16x16x32_bf16 v[48:51], v[228:231], v[188:191], v[48:51]
	v_mfma_f32_16x16x32_bf16 v[32:35], v[228:231], v[196:199], v[32:35]
	s_waitcnt lgkmcnt(1)
	v_mfma_f32_16x16x32_bf16 v[44:47], v[232:235], v[188:191], v[44:47]
	v_mfma_f32_16x16x32_bf16 v[28:31], v[232:235], v[196:199], v[28:31]
	s_waitcnt lgkmcnt(0)
	v_mfma_f32_16x16x32_bf16 v[40:43], v[236:239], v[188:191], v[40:43]
	v_mfma_f32_16x16x32_bf16 v[24:27], v[236:239], v[196:199], v[24:27]
	v_cmp_ne_u32_e32 vcc, v141, v143
	v_mov_b32_e32 v88, v103
	v_mov_b32_e32 v97, v102
	v_pk_add_f32 v[100:101], v[100:101], v[220:221]
	s_branch .Ln2_tail
